# fp8 table preparation: per-row amax ds_bpermute butterflies replaced by permlane swaps and DPP row rotations (both copies of the prep part 1 block)
# speedup vs baseline: 1.0069x; 1.0032x over previous
; template <int NR>
; DI void fp8_rows(const float* __restrict__ src, unsigned char* __restrict__ dst, float* __restrict__ scale_out, int lane) {
;   float4 v[NR][4];
; #pragma unroll
;   for (int r = 0; r < NR; ++r)
; #pragma unroll
;     for (int i = 0; i < 4; ++i) v[r][i] = *(const float4*)(src + (size_t)r * 1024 + 256 * i + lane * 4);
; #pragma unroll
;   for (int r = 0; r < NR; ++r) {
;     float amax = 0.f;
; #pragma unroll
;     for (int i = 0; i < 4; ++i)
;       amax = fmaxf(amax, fmaxf(fmaxf(fabsf(v[r][i].x), fabsf(v[r][i].y)), fmaxf(fabsf(v[r][i].z), fabsf(v[r][i].w))));
; #pragma unroll
;     for (int o = 32; o > 0; o >>= 1) amax = fmaxf(amax, __shfl_xor(amax, o));
;     const float scale = amax > 0.f ? amax * (1.f / 440.f) : 1.f;
;     const float inv = 1.f / scale;
;     u32x4 w;
; #pragma unroll
;     for (int i = 0; i < 4; ++i) {
;       int t = 0;
;       t = __builtin_amdgcn_cvt_pk_fp8_f32(v[r][i].x * inv, v[r][i].y * inv, t, false);
;       t = __builtin_amdgcn_cvt_pk_fp8_f32(v[r][i].z * inv, v[r][i].w * inv, t, true);
;       w[i] = (unsigned)t;
;     }
;     *(u32x4*)(dst + (size_t)r * 1024 + lane * 16) = w;
;     if (lane == 0) scale_out[r] = scale;
;   }
; }
; DI void phase_prep(const Params& p, char* smem, int part, int vb) {
;     ...
;       if (it < 1024) {
;         int row = it * 16 + wave * 4;
;         fp8_rows<4>(p.pu + (size_t)row * 1024, (unsigned char*)(ws + WS_UBF) + (size_t)row * 1024, (float*)(ws + WS_SU) + row, lane);
;         continue;
;       }
;       it -= 1024;
;       if (it < 1024) {
;         int row = it * 16 + wave * 4;
;         fp8_rows<4>(p.pv + (size_t)row * 1024, (unsigned char*)(ws + WS_VBF) + (size_t)row * 1024, (float*)(ws + WS_SV) + row, lane);
;         continue;
;       }
.Lp1a_457:
	s_andn2_b64 vcc, exec, s[12:13]
	s_cbranch_vccnz .Lp1a_467
	v_lshl_add_u32 v88, s20, 4, v63
	v_ashrrev_i32_e32 v89, 31, v88
	v_lshlrev_b64 v[0:1], 12, v[88:89]
	v_lshl_add_u64 v[0:1], v[54:55], 0, v[0:1]
	global_load_dwordx4 v[58:61], v[0:1], off
	global_load_dwordx4 v[72:75], v[0:1], off offset:1024
	global_load_dwordx4 v[76:79], v[0:1], off offset:2048
	global_load_dwordx4 v[80:83], v[0:1], off offset:3072
	v_and_b32_e32 v2, 64, v65
	v_xor_b32_e32 v3, 32, v65
	v_add_u32_e32 v70, 64, v2
	v_xor_b32_e32 v4, 16, v65
	v_cmp_lt_i32_e32 vcc, v3, v70
	v_xor_b32_e32 v67, 8, v65
	s_waitcnt vmcnt(4)
	v_xor_b32_e32 v85, 1, v65
	v_cndmask_b32_e32 v2, v65, v3, vcc
	v_cmp_lt_i32_e32 vcc, v4, v70
	v_lshlrev_b32_e32 v66, 2, v2
	v_mov_b32_e32 v86, 0
	v_cndmask_b32_e32 v3, v65, v4, vcc
	v_add_co_u32_e32 v2, vcc, s31, v0
	v_lshlrev_b32_e32 v48, 2, v3
	s_nop 0
	v_addc_co_u32_e32 v3, vcc, 0, v1, vcc
	v_add_co_u32_e32 v44, vcc, s34, v0
	global_load_dwordx4 v[36:39], v[2:3], off offset:1024
	global_load_dwordx4 v[32:35], v[2:3], off offset:2048
	v_addc_co_u32_e32 v45, vcc, 0, v1, vcc
	v_add_co_u32_e32 v0, vcc, s35, v0
	global_load_dwordx4 v[28:31], v[44:45], off
	global_load_dwordx4 v[24:27], v[44:45], off offset:1024
	global_load_dwordx4 v[20:23], v[44:45], off offset:2048
	global_load_dwordx4 v[16:19], v[44:45], off offset:3072
	v_addc_co_u32_e32 v1, vcc, 0, v1, vcc
	v_cmp_lt_i32_e32 vcc, v67, v70
	s_waitcnt vmcnt(9)
	v_max_f32_e64 v4, |v61|, |v61|
	v_max_f32_e64 v5, |v60|, |v60|
	s_waitcnt vmcnt(8)
	v_max_f32_e64 v6, |v75|, |v75|
	v_max_f32_e64 v7, |v74|, |v74|
	s_waitcnt vmcnt(7)
	v_max_f32_e64 v8, |v79|, |v79|
	v_max_f32_e64 v9, |v78|, |v78|
	s_waitcnt vmcnt(6)
	v_max_f32_e64 v10, |v83|, |v83|
	v_max_f32_e64 v11, |v82|, |v82|
	v_max_f32_e32 v4, v5, v4
	v_max_f32_e32 v5, v7, v6
	v_max_f32_e32 v6, v9, v8
	v_max_f32_e32 v7, v11, v10
	v_max3_f32 v4, |v58|, |v59|, v4
	v_max3_f32 v5, |v72|, |v73|, v5
	v_max3_f32 v6, |v76|, |v77|, v6
	v_max3_f32 v7, |v80|, |v81|, v7
	v_max3_f32 v4, v4, 0, v5
	v_max3_f32 v46, v4, v6, v7
	v_mov_b32_e32 v47, v46
	s_nop 1
	v_permlane32_swap_b32_e32 v47, v46
	s_nop 1
	global_load_dwordx4 v[40:43], v[2:3], off offset:3072
	global_load_dwordx4 v[12:15], v[0:1], off
	global_load_dwordx4 v[8:11], v[0:1], off offset:1024
	global_load_dwordx4 v[4:7], v[0:1], off offset:2048
	v_cndmask_b32_e32 v67, v65, v67, vcc
	v_lshlrev_b32_e32 v67, 2, v67
	s_waitcnt lgkmcnt(0)
	v_max_f32_e32 v2, v47, v47
	v_max_f32_e32 v68, v46, v2
	global_load_dwordx4 v[44:47], v[44:45], off offset:-4096
	s_nop 0
	global_load_dwordx4 v[0:3], v[0:1], off offset:3072
	v_mov_b32_e32 v69, v68
	s_nop 1
	v_permlane16_swap_b32_e32 v69, v68
	s_nop 1
	s_waitcnt lgkmcnt(0)
	v_max_f32_e32 v69, v69, v69
	v_max_f32_e32 v69, v68, v69
	s_nop 1
	v_mov_b32_dpp v71, v69 row_ror:8 row_mask:0xf bank_mask:0xf
	s_nop 0
	v_xor_b32_e32 v68, 4, v65
	v_cmp_lt_i32_e32 vcc, v68, v70
	s_waitcnt lgkmcnt(0)
	v_max_f32_e32 v71, v71, v71
	v_cndmask_b32_e32 v68, v65, v68, vcc
	v_lshlrev_b32_e32 v68, 2, v68
	v_max_f32_e32 v71, v69, v71
	s_nop 1
	v_mov_b32_dpp v84, v71 row_ror:4 row_mask:0xf bank_mask:0xf
	s_nop 0
	v_xor_b32_e32 v69, 2, v65
	v_cmp_lt_i32_e32 vcc, v69, v70
	s_waitcnt lgkmcnt(0)
	v_max_f32_e32 v84, v84, v84
	v_cndmask_b32_e32 v69, v65, v69, vcc
	v_lshlrev_b32_e32 v69, 2, v69
	v_max_f32_e32 v71, v71, v84
	s_nop 1
	v_mov_b32_dpp v84, v71 row_ror:2 row_mask:0xf bank_mask:0xf
	s_nop 0
	v_cmp_lt_i32_e32 vcc, v85, v70
	s_waitcnt lgkmcnt(0)
	v_max_f32_e32 v84, v84, v84
	v_cndmask_b32_e32 v70, v65, v85, vcc
	v_lshlrev_b32_e32 v70, 2, v70
	v_max_f32_e32 v71, v71, v84
	s_nop 1
	v_mov_b32_dpp v87, v71 row_ror:1 row_mask:0xf bank_mask:0xf
	s_nop 0
	v_mov_b32_e32 v84, 0
	v_mov_b32_e32 v85, 0
	s_waitcnt lgkmcnt(0)
	v_max_f32_e32 v87, v87, v87
	v_max_f32_e32 v71, v71, v87
	v_mul_f32_e32 v87, 0x3b14f209, v71
	v_cmp_lt_f32_e32 vcc, 0, v71
	s_nop 1
	v_cndmask_b32_e32 v71, 1.0, v87, vcc
	v_div_scale_f32 v90, s[12:13], v71, v71, 1.0
	v_rcp_f32_e32 v91, v90
	v_div_scale_f32 v92, vcc, 1.0, v71, 1.0
	v_mov_b32_e32 v87, 0
	v_fma_f32 v93, -v90, v91, 1.0
	v_fmac_f32_e32 v91, v93, v91
	v_mul_f32_e32 v93, v92, v91
	v_fma_f32 v94, -v90, v93, v92
	v_fmac_f32_e32 v93, v94, v91
	v_fma_f32 v90, -v90, v93, v92
	v_div_fmas_f32 v90, v90, v91, v93
	v_div_fixup_f32 v90, v90, v71, 1.0
	v_mul_f32_e32 v58, v58, v90
	v_mul_f32_e32 v59, v59, v90
	v_mul_f32_e32 v72, v72, v90
	v_mul_f32_e32 v73, v73, v90
	v_mul_f32_e32 v76, v76, v90
	v_mul_f32_e32 v77, v77, v90
	v_mul_f32_e32 v80, v80, v90
	v_mul_f32_e32 v81, v81, v90
	v_cvt_pk_fp8_f32 v84, v58, v59
	v_cvt_pk_fp8_f32 v85, v72, v73
	v_cvt_pk_fp8_f32 v86, v76, v77
	v_cvt_pk_fp8_f32 v87, v80, v81
	v_mul_f32_e32 v60, v60, v90
	v_mul_f32_e32 v61, v61, v90
	v_mul_f32_e32 v74, v74, v90
	v_mul_f32_e32 v75, v75, v90
	v_mul_f32_e32 v78, v78, v90
	v_mul_f32_e32 v79, v79, v90
	v_mul_f32_e32 v82, v82, v90
	v_mul_f32_e32 v83, v83, v90
	v_cvt_pk_fp8_f32 v84, v60, v61 op_sel:[0,0,1]
	v_cvt_pk_fp8_f32 v85, v74, v75 op_sel:[0,0,1]
	v_cvt_pk_fp8_f32 v86, v78, v79 op_sel:[0,0,1]
	v_cvt_pk_fp8_f32 v87, v82, v83 op_sel:[0,0,1]
	v_lshlrev_b64 v[60:61], 10, v[88:89]
	v_lshl_add_u64 v[58:59], v[88:89], 3, s[8:9]
	v_lshl_add_u64 v[60:61], v[50:51], 0, v[60:61]
	global_store_dwordx4 v[60:61], v[84:87], off
	s_and_saveexec_b64 s[12:13], s[4:5]
	s_cbranch_execz .Lp1a_460
	global_store_dword v[58:59], v71, off
; template <int NR>
; DI void fp8_rows(const float* __restrict__ src, unsigned char* __restrict__ dst, float* __restrict__ scale_out, int lane) {
;     ...
;   for (int r = 0; r < NR; ++r) {
;     float amax = 0.f;
; #pragma unroll
;     for (int i = 0; i < 4; ++i)
;       amax = fmaxf(amax, fmaxf(fmaxf(fabsf(v[r][i].x), fabsf(v[r][i].y)), fmaxf(fabsf(v[r][i].z), fabsf(v[r][i].w))));
; #pragma unroll
;     for (int o = 32; o > 0; o >>= 1) amax = fmaxf(amax, __shfl_xor(amax, o));
;     const float scale = amax > 0.f ? amax * (1.f / 440.f) : 1.f;
;     const float inv = 1.f / scale;
;     u32x4 w;
; #pragma unroll
;     for (int i = 0; i < 4; ++i) {
;       int t = 0;
;       t = __builtin_amdgcn_cvt_pk_fp8_f32(v[r][i].x * inv, v[r][i].y * inv, t, false);
;       t = __builtin_amdgcn_cvt_pk_fp8_f32(v[r][i].z * inv, v[r][i].w * inv, t, true);
;       w[i] = (unsigned)t;
;     }
;     *(u32x4*)(dst + (size_t)r * 1024 + lane * 16) = w;
;     if (lane == 0) scale_out[r] = scale;
;   }
.Lp1a_460:
	s_or_b64 exec, exec, s[12:13]
	s_waitcnt vmcnt(2)
	v_max_f32_e64 v71, |v47|, |v47|
	v_max_f32_e64 v72, |v46|, |v46|
	v_max_f32_e32 v71, v72, v71
	v_max_f32_e64 v72, |v39|, |v39|
	v_max_f32_e64 v73, |v38|, |v38|
	v_max_f32_e32 v72, v73, v72
	v_max3_f32 v71, |v44|, |v45|, v71
	v_max3_f32 v72, |v36|, |v37|, v72
	v_max3_f32 v71, v71, 0, v72
	v_max_f32_e64 v72, |v35|, |v35|
	v_max_f32_e64 v73, |v34|, |v34|
	v_max_f32_e32 v72, v73, v72
	v_max_f32_e64 v73, |v43|, |v43|
	v_max_f32_e64 v74, |v42|, |v42|
	v_max_f32_e32 v73, v74, v73
	v_max3_f32 v72, |v32|, |v33|, v72
	v_max3_f32 v73, |v40|, |v41|, v73
	v_max3_f32 v71, v71, v72, v73
	v_mov_b32_e32 v72, v71
	s_nop 1
	v_permlane32_swap_b32_e32 v72, v71
	s_nop 1
	s_waitcnt lgkmcnt(0)
	v_max_f32_e32 v72, v72, v72
	v_max_f32_e32 v71, v71, v72
	v_mov_b32_e32 v72, v71
	s_nop 1
	v_permlane16_swap_b32_e32 v72, v71
	s_nop 1
	s_waitcnt lgkmcnt(0)
	v_max_f32_e32 v72, v72, v72
	v_max_f32_e32 v71, v71, v72
	s_nop 1
	v_mov_b32_dpp v72, v71 row_ror:8 row_mask:0xf bank_mask:0xf
	s_nop 0
	s_waitcnt lgkmcnt(0)
	v_max_f32_e32 v72, v72, v72
	v_max_f32_e32 v71, v71, v72
	s_nop 1
	v_mov_b32_dpp v72, v71 row_ror:4 row_mask:0xf bank_mask:0xf
	s_nop 0
	s_waitcnt lgkmcnt(0)
	v_max_f32_e32 v72, v72, v72
	v_max_f32_e32 v71, v71, v72
	s_nop 1
	v_mov_b32_dpp v72, v71 row_ror:2 row_mask:0xf bank_mask:0xf
	s_nop 0
	s_waitcnt lgkmcnt(0)
	v_max_f32_e32 v72, v72, v72
	v_max_f32_e32 v71, v71, v72
	s_nop 1
	v_mov_b32_dpp v73, v71 row_ror:1 row_mask:0xf bank_mask:0xf
	s_nop 0
	v_mov_b32_e32 v72, 0
	s_waitcnt lgkmcnt(0)
	v_max_f32_e32 v73, v73, v73
	v_max_f32_e32 v71, v71, v73
	v_mul_f32_e32 v73, 0x3b14f209, v71
	v_cmp_lt_f32_e32 vcc, 0, v71
	s_nop 1
	v_cndmask_b32_e32 v71, 1.0, v73, vcc
	v_div_scale_f32 v74, s[12:13], v71, v71, 1.0
	v_rcp_f32_e32 v75, v74
	v_div_scale_f32 v76, vcc, 1.0, v71, 1.0
	v_mov_b32_e32 v73, 0
	v_fma_f32 v77, -v74, v75, 1.0
	v_fmac_f32_e32 v75, v77, v75
	v_mul_f32_e32 v77, v76, v75
	v_fma_f32 v78, -v74, v77, v76
	v_fmac_f32_e32 v77, v78, v75
	v_fma_f32 v74, -v74, v77, v76
	v_div_fmas_f32 v74, v74, v75, v77
	v_div_fixup_f32 v76, v74, v71, 1.0
	v_mul_f32_e32 v32, v32, v76
	v_mul_f32_e32 v33, v33, v76
	v_mov_b32_e32 v74, 0
	v_mul_f32_e32 v44, v44, v76
	v_mul_f32_e32 v45, v45, v76
	v_mul_f32_e32 v36, v36, v76
	v_mul_f32_e32 v37, v37, v76
	v_cvt_pk_fp8_f32 v74, v32, v33
	v_mul_f32_e32 v32, v34, v76
	v_mul_f32_e32 v33, v35, v76
	v_mul_f32_e32 v34, v40, v76
	v_mul_f32_e32 v35, v41, v76
	v_mov_b32_e32 v75, 0
	v_cvt_pk_fp8_f32 v72, v44, v45
	v_cvt_pk_fp8_f32 v73, v36, v37
	v_cvt_pk_fp8_f32 v75, v34, v35
	v_mul_f32_e32 v46, v46, v76
	v_mul_f32_e32 v47, v47, v76
	v_mul_f32_e32 v38, v38, v76
	v_mul_f32_e32 v36, v39, v76
	v_cvt_pk_fp8_f32 v74, v32, v33 op_sel:[0,0,1]
	v_mul_f32_e32 v32, v42, v76
	v_mul_f32_e32 v33, v43, v76
	v_cvt_pk_fp8_f32 v72, v46, v47 op_sel:[0,0,1]
	v_cvt_pk_fp8_f32 v73, v38, v36 op_sel:[0,0,1]
	v_cvt_pk_fp8_f32 v75, v32, v33 op_sel:[0,0,1]
	global_store_dwordx4 v[60:61], v[72:75], off offset:1024
	s_and_saveexec_b64 s[12:13], s[4:5]
	s_cbranch_execz .Lp1a_462
	global_store_dword v[58:59], v71, off offset:8
; template <int NR>
; DI void fp8_rows(const float* __restrict__ src, unsigned char* __restrict__ dst, float* __restrict__ scale_out, int lane) {
;     ...
;   for (int r = 0; r < NR; ++r) {
;     float amax = 0.f;
; #pragma unroll
;     for (int i = 0; i < 4; ++i)
;       amax = fmaxf(amax, fmaxf(fmaxf(fabsf(v[r][i].x), fabsf(v[r][i].y)), fmaxf(fabsf(v[r][i].z), fabsf(v[r][i].w))));
; #pragma unroll
;     for (int o = 32; o > 0; o >>= 1) amax = fmaxf(amax, __shfl_xor(amax, o));
;     const float scale = amax > 0.f ? amax * (1.f / 440.f) : 1.f;
;     const float inv = 1.f / scale;
;     u32x4 w;
; #pragma unroll
;     for (int i = 0; i < 4; ++i) {
;       int t = 0;
;       t = __builtin_amdgcn_cvt_pk_fp8_f32(v[r][i].x * inv, v[r][i].y * inv, t, false);
;       t = __builtin_amdgcn_cvt_pk_fp8_f32(v[r][i].z * inv, v[r][i].w * inv, t, true);
;       w[i] = (unsigned)t;
;     }
;     *(u32x4*)(dst + (size_t)r * 1024 + lane * 16) = w;
;     if (lane == 0) scale_out[r] = scale;
;   }
.Lp1a_462:
	s_or_b64 exec, exec, s[12:13]
	v_max_f32_e64 v32, |v31|, |v31|
	v_max_f32_e64 v33, |v30|, |v30|
	v_max_f32_e32 v32, v33, v32
	v_max_f32_e64 v33, |v27|, |v27|
	v_max_f32_e64 v34, |v26|, |v26|
	v_max_f32_e32 v33, v34, v33
	v_max3_f32 v32, |v28|, |v29|, v32
	v_max3_f32 v33, |v24|, |v25|, v33
	v_max3_f32 v32, v32, 0, v33
	v_max_f32_e64 v33, |v23|, |v23|
	v_max_f32_e64 v34, |v22|, |v22|
	v_max_f32_e32 v33, v34, v33
	v_max_f32_e64 v34, |v19|, |v19|
	v_max_f32_e64 v35, |v18|, |v18|
	v_max_f32_e32 v34, v35, v34
	v_max3_f32 v33, |v20|, |v21|, v33
	v_max3_f32 v34, |v16|, |v17|, v34
	v_max3_f32 v32, v32, v33, v34
	v_mov_b32_e32 v33, v32
	s_nop 1
	v_permlane32_swap_b32_e32 v33, v32
	s_nop 1
	v_mov_b32_e32 v34, 0
	v_mov_b32_e32 v35, 0
	s_waitcnt lgkmcnt(0)
	v_max_f32_e32 v33, v33, v33
	v_max_f32_e32 v32, v32, v33
	v_mov_b32_e32 v33, v32
	s_nop 1
	v_permlane16_swap_b32_e32 v33, v32
	s_nop 1
	s_waitcnt lgkmcnt(0)
	v_max_f32_e32 v33, v33, v33
	v_max_f32_e32 v32, v32, v33
	s_nop 1
	v_mov_b32_dpp v33, v32 row_ror:8 row_mask:0xf bank_mask:0xf
	s_nop 0
	s_waitcnt lgkmcnt(0)
	v_max_f32_e32 v33, v33, v33
	v_max_f32_e32 v32, v32, v33
	s_nop 1
	v_mov_b32_dpp v33, v32 row_ror:4 row_mask:0xf bank_mask:0xf
	s_nop 0
	s_waitcnt lgkmcnt(0)
	v_max_f32_e32 v33, v33, v33
	v_max_f32_e32 v32, v32, v33
	s_nop 1
	v_mov_b32_dpp v33, v32 row_ror:2 row_mask:0xf bank_mask:0xf
	s_nop 0
	s_waitcnt lgkmcnt(0)
	v_max_f32_e32 v33, v33, v33
	v_max_f32_e32 v32, v32, v33
	s_nop 1
	v_mov_b32_dpp v33, v32 row_ror:1 row_mask:0xf bank_mask:0xf
	s_nop 0
	s_waitcnt lgkmcnt(0)
	v_max_f32_e32 v33, v33, v33
	v_max_f32_e32 v32, v32, v33
	v_mul_f32_e32 v33, 0x3b14f209, v32
	v_cmp_lt_f32_e32 vcc, 0, v32
	s_nop 1
	v_cndmask_b32_e32 v32, 1.0, v33, vcc
	v_div_scale_f32 v33, s[12:13], v32, v32, 1.0
	v_rcp_f32_e32 v36, v33
	v_div_scale_f32 v37, vcc, 1.0, v32, 1.0
	v_fma_f32 v38, -v33, v36, 1.0
	v_fmac_f32_e32 v36, v38, v36
	v_mul_f32_e32 v38, v37, v36
	v_fma_f32 v39, -v33, v38, v37
	v_fmac_f32_e32 v38, v39, v36
	v_fma_f32 v33, -v33, v38, v37
	v_div_fmas_f32 v33, v33, v36, v38
	v_div_fixup_f32 v33, v33, v32, 1.0
	v_mul_f32_e32 v28, v28, v33
	v_mul_f32_e32 v29, v29, v33
	v_mul_f32_e32 v24, v24, v33
	v_mul_f32_e32 v25, v25, v33
	v_mul_f32_e32 v20, v20, v33
	v_mul_f32_e32 v21, v21, v33
	v_mov_b32_e32 v36, 0
	v_mul_f32_e32 v16, v16, v33
	v_mul_f32_e32 v17, v17, v33
	v_mov_b32_e32 v37, 0
	v_cvt_pk_fp8_f32 v34, v28, v29
	v_cvt_pk_fp8_f32 v35, v24, v25
	v_cvt_pk_fp8_f32 v36, v20, v21
	v_cvt_pk_fp8_f32 v37, v16, v17
	v_mul_f32_e32 v30, v30, v33
	v_mul_f32_e32 v31, v31, v33
	v_mul_f32_e32 v26, v26, v33
	v_mul_f32_e32 v24, v27, v33
	v_mul_f32_e32 v20, v22, v33
	v_mul_f32_e32 v21, v23, v33
	v_mul_f32_e32 v16, v18, v33
	v_mul_f32_e32 v17, v19, v33
	v_cvt_pk_fp8_f32 v34, v30, v31 op_sel:[0,0,1]
	v_cvt_pk_fp8_f32 v35, v26, v24 op_sel:[0,0,1]
	v_cvt_pk_fp8_f32 v36, v20, v21 op_sel:[0,0,1]
	v_cvt_pk_fp8_f32 v37, v16, v17 op_sel:[0,0,1]
	global_store_dwordx4 v[60:61], v[34:37], off offset:2048
	s_and_saveexec_b64 s[12:13], s[4:5]
	s_cbranch_execz .Lp1a_464
	global_store_dword v[58:59], v32, off offset:16
.Lp1a_464:
	s_or_b64 exec, exec, s[12:13]
	v_max_f32_e64 v16, |v15|, |v15|
	v_max_f32_e64 v17, |v14|, |v14|
	v_max_f32_e32 v16, v17, v16
	v_max_f32_e64 v17, |v11|, |v11|
	v_max_f32_e64 v18, |v10|, |v10|
	v_max_f32_e32 v17, v18, v17
	v_max3_f32 v16, |v12|, |v13|, v16
	v_max3_f32 v17, |v8|, |v9|, v17
	v_max3_f32 v16, v16, 0, v17
	v_max_f32_e64 v17, |v7|, |v7|
	v_max_f32_e64 v18, |v6|, |v6|
	v_max_f32_e32 v17, v18, v17
	s_waitcnt vmcnt(3)
	v_max_f32_e64 v18, |v3|, |v3|
	v_max_f32_e64 v19, |v2|, |v2|
	v_max_f32_e32 v18, v19, v18
	v_max3_f32 v17, |v4|, |v5|, v17
	v_max3_f32 v18, |v0|, |v1|, v18
	v_max3_f32 v16, v16, v17, v18
	v_mov_b32_e32 v17, v16
	s_nop 1
	v_permlane32_swap_b32_e32 v17, v16
	s_nop 1
	v_mov_b32_e32 v18, 0
	v_mov_b32_e32 v19, 0
	s_waitcnt lgkmcnt(0)
	v_max_f32_e32 v17, v17, v17
	v_max_f32_e32 v16, v16, v17
	v_mov_b32_e32 v17, v16
	s_nop 1
	v_permlane16_swap_b32_e32 v17, v16
	s_nop 1
	s_waitcnt lgkmcnt(0)
	v_max_f32_e32 v17, v17, v17
	v_max_f32_e32 v16, v16, v17
	s_nop 1
	v_mov_b32_dpp v17, v16 row_ror:8 row_mask:0xf bank_mask:0xf
	s_nop 0
	s_waitcnt lgkmcnt(0)
	v_max_f32_e32 v17, v17, v17
	v_max_f32_e32 v16, v16, v17
	s_nop 1
	v_mov_b32_dpp v17, v16 row_ror:4 row_mask:0xf bank_mask:0xf
	s_nop 0
	s_waitcnt lgkmcnt(0)
	v_max_f32_e32 v17, v17, v17
	v_max_f32_e32 v16, v16, v17
	s_nop 1
	v_mov_b32_dpp v17, v16 row_ror:2 row_mask:0xf bank_mask:0xf
	s_nop 0
	s_waitcnt lgkmcnt(0)
	v_max_f32_e32 v17, v17, v17
	v_max_f32_e32 v16, v16, v17
	s_nop 1
	v_mov_b32_dpp v17, v16 row_ror:1 row_mask:0xf bank_mask:0xf
	s_nop 0
	s_waitcnt lgkmcnt(0)
	v_max_f32_e32 v17, v17, v17
	v_max_f32_e32 v16, v16, v17
	v_mul_f32_e32 v17, 0x3b14f209, v16
	v_cmp_lt_f32_e32 vcc, 0, v16
	s_nop 1
	v_cndmask_b32_e32 v16, 1.0, v17, vcc
	v_div_scale_f32 v17, s[12:13], v16, v16, 1.0
	v_rcp_f32_e32 v20, v17
	v_div_scale_f32 v21, vcc, 1.0, v16, 1.0
	v_fma_f32 v22, -v17, v20, 1.0
	v_fmac_f32_e32 v20, v22, v20
	v_mul_f32_e32 v22, v21, v20
	v_fma_f32 v23, -v17, v22, v21
	v_fmac_f32_e32 v22, v23, v20
	v_fma_f32 v17, -v17, v22, v21
	v_div_fmas_f32 v17, v17, v20, v22
	v_div_fixup_f32 v17, v17, v16, 1.0
	v_mul_f32_e32 v12, v12, v17
	v_mul_f32_e32 v13, v13, v17
	v_mul_f32_e32 v8, v8, v17
	v_mul_f32_e32 v9, v9, v17
	v_mul_f32_e32 v4, v4, v17
	v_mul_f32_e32 v5, v5, v17
	v_mov_b32_e32 v20, 0
	v_mul_f32_e32 v0, v0, v17
	v_mul_f32_e32 v1, v1, v17
	v_mov_b32_e32 v21, 0
	v_cvt_pk_fp8_f32 v18, v12, v13
	v_cvt_pk_fp8_f32 v19, v8, v9
	v_cvt_pk_fp8_f32 v20, v4, v5
	v_cvt_pk_fp8_f32 v21, v0, v1
	v_mul_f32_e32 v14, v14, v17
	v_mul_f32_e32 v15, v15, v17
	v_mul_f32_e32 v10, v10, v17
	v_mul_f32_e32 v8, v11, v17
	v_mul_f32_e32 v4, v6, v17
	v_mul_f32_e32 v5, v7, v17
	v_mul_f32_e32 v0, v2, v17
	v_mul_f32_e32 v1, v3, v17
	v_cvt_pk_fp8_f32 v18, v14, v15 op_sel:[0,0,1]
	v_cvt_pk_fp8_f32 v19, v10, v8 op_sel:[0,0,1]
	v_cvt_pk_fp8_f32 v20, v4, v5 op_sel:[0,0,1]
	v_cvt_pk_fp8_f32 v21, v0, v1 op_sel:[0,0,1]
	global_store_dwordx4 v[60:61], v[18:21], off offset:3072
	s_and_saveexec_b64 s[12:13], s[4:5]
	s_cbranch_execz .Lp1a_466
	global_store_dword v[58:59], v16, off offset:24

; template <int NR>
; DI void fp8_rows(const float* __restrict__ src, unsigned char* __restrict__ dst, float* __restrict__ scale_out, int lane) {
;   float4 v[NR][4];
; #pragma unroll
;   for (int r = 0; r < NR; ++r)
; #pragma unroll
;     for (int i = 0; i < 4; ++i) v[r][i] = *(const float4*)(src + (size_t)r * 1024 + 256 * i + lane * 4);
; #pragma unroll
;   for (int r = 0; r < NR; ++r) {
;     float amax = 0.f;
; #pragma unroll
;     for (int i = 0; i < 4; ++i)
;       amax = fmaxf(amax, fmaxf(fmaxf(fabsf(v[r][i].x), fabsf(v[r][i].y)), fmaxf(fabsf(v[r][i].z), fabsf(v[r][i].w))));
; #pragma unroll
;     for (int o = 32; o > 0; o >>= 1) amax = fmaxf(amax, __shfl_xor(amax, o));
;     const float scale = amax > 0.f ? amax * (1.f / 440.f) : 1.f;
;     const float inv = 1.f / scale;
;     u32x4 w;
; #pragma unroll
;     for (int i = 0; i < 4; ++i) {
;       int t = 0;
;       t = __builtin_amdgcn_cvt_pk_fp8_f32(v[r][i].x * inv, v[r][i].y * inv, t, false);
;       t = __builtin_amdgcn_cvt_pk_fp8_f32(v[r][i].z * inv, v[r][i].w * inv, t, true);
;       w[i] = (unsigned)t;
;     }
;     *(u32x4*)(dst + (size_t)r * 1024 + lane * 16) = w;
;     if (lane == 0) scale_out[r] = scale;
;   }
; }
; DI void phase_prep(const Params& p, char* smem, int part, int vb) {
;     ...
;       if (it < 1024) {
;         int row = it * 16 + wave * 4;
;         fp8_rows<4>(p.pv + (size_t)row * 1024, (unsigned char*)(ws + WS_VBF) + (size_t)row * 1024, (float*)(ws + WS_SV) + row, lane);
;         continue;
;       }
.Lp1a_469:
	v_lshl_add_u32 v88, s20, 4, v62
	v_ashrrev_i32_e32 v89, 31, v88
	v_lshlrev_b64 v[0:1], 12, v[88:89]
	v_lshl_add_u64 v[0:1], v[56:57], 0, v[0:1]
	global_load_dwordx4 v[58:61], v[0:1], off
	global_load_dwordx4 v[72:75], v[0:1], off offset:1024
	global_load_dwordx4 v[76:79], v[0:1], off offset:2048
	global_load_dwordx4 v[80:83], v[0:1], off offset:3072
	v_and_b32_e32 v2, 64, v65
	v_xor_b32_e32 v3, 32, v65
	v_add_u32_e32 v70, 64, v2
	v_xor_b32_e32 v4, 16, v65
	v_cmp_lt_i32_e32 vcc, v3, v70
	v_xor_b32_e32 v67, 8, v65
	s_waitcnt vmcnt(4)
	v_xor_b32_e32 v85, 1, v65
	v_cndmask_b32_e32 v2, v65, v3, vcc
	v_cmp_lt_i32_e32 vcc, v4, v70
	v_lshlrev_b32_e32 v66, 2, v2
	v_mov_b32_e32 v86, 0
	v_cndmask_b32_e32 v3, v65, v4, vcc
	v_add_co_u32_e32 v2, vcc, s31, v0
	v_lshlrev_b32_e32 v48, 2, v3
	s_nop 0
	v_addc_co_u32_e32 v3, vcc, 0, v1, vcc
	v_add_co_u32_e32 v44, vcc, s34, v0
	global_load_dwordx4 v[36:39], v[2:3], off offset:1024
	global_load_dwordx4 v[32:35], v[2:3], off offset:2048
	v_addc_co_u32_e32 v45, vcc, 0, v1, vcc
	v_add_co_u32_e32 v0, vcc, s35, v0
	global_load_dwordx4 v[28:31], v[44:45], off
	global_load_dwordx4 v[24:27], v[44:45], off offset:1024
	global_load_dwordx4 v[20:23], v[44:45], off offset:2048
	global_load_dwordx4 v[16:19], v[44:45], off offset:3072
	v_addc_co_u32_e32 v1, vcc, 0, v1, vcc
	v_cmp_lt_i32_e32 vcc, v67, v70
	s_waitcnt vmcnt(9)
	v_max_f32_e64 v4, |v61|, |v61|
	v_max_f32_e64 v5, |v60|, |v60|
	s_waitcnt vmcnt(8)
	v_max_f32_e64 v6, |v75|, |v75|
	v_max_f32_e64 v7, |v74|, |v74|
	s_waitcnt vmcnt(7)
	v_max_f32_e64 v8, |v79|, |v79|
	v_max_f32_e64 v9, |v78|, |v78|
	s_waitcnt vmcnt(6)
	v_max_f32_e64 v10, |v83|, |v83|
	v_max_f32_e64 v11, |v82|, |v82|
	v_max_f32_e32 v4, v5, v4
	v_max_f32_e32 v5, v7, v6
	v_max_f32_e32 v6, v9, v8
	v_max_f32_e32 v7, v11, v10
	v_max3_f32 v4, |v58|, |v59|, v4
	v_max3_f32 v5, |v72|, |v73|, v5
	v_max3_f32 v6, |v76|, |v77|, v6
	v_max3_f32 v7, |v80|, |v81|, v7
	v_max3_f32 v4, v4, 0, v5
	v_max3_f32 v46, v4, v6, v7
	v_mov_b32_e32 v47, v46
	s_nop 1
	v_permlane32_swap_b32_e32 v47, v46
	s_nop 1
	global_load_dwordx4 v[40:43], v[2:3], off offset:3072
	global_load_dwordx4 v[12:15], v[0:1], off
	global_load_dwordx4 v[8:11], v[0:1], off offset:1024
	global_load_dwordx4 v[4:7], v[0:1], off offset:2048
	v_cndmask_b32_e32 v67, v65, v67, vcc
	v_lshlrev_b32_e32 v67, 2, v67
	s_waitcnt lgkmcnt(0)
	v_max_f32_e32 v2, v47, v47
	v_max_f32_e32 v68, v46, v2
	global_load_dwordx4 v[44:47], v[44:45], off offset:-4096
	s_nop 0
	global_load_dwordx4 v[0:3], v[0:1], off offset:3072
	v_mov_b32_e32 v69, v68
	s_nop 1
	v_permlane16_swap_b32_e32 v69, v68
	s_nop 1
	s_waitcnt lgkmcnt(0)
	v_max_f32_e32 v69, v69, v69
	v_max_f32_e32 v69, v68, v69
	s_nop 1
	v_mov_b32_dpp v71, v69 row_ror:8 row_mask:0xf bank_mask:0xf
	s_nop 0
	v_xor_b32_e32 v68, 4, v65
	v_cmp_lt_i32_e32 vcc, v68, v70
	s_waitcnt lgkmcnt(0)
	v_max_f32_e32 v71, v71, v71
	v_cndmask_b32_e32 v68, v65, v68, vcc
	v_lshlrev_b32_e32 v68, 2, v68
	v_max_f32_e32 v71, v69, v71
	s_nop 1
	v_mov_b32_dpp v84, v71 row_ror:4 row_mask:0xf bank_mask:0xf
	s_nop 0
	v_xor_b32_e32 v69, 2, v65
	v_cmp_lt_i32_e32 vcc, v69, v70
	s_waitcnt lgkmcnt(0)
	v_max_f32_e32 v84, v84, v84
	v_cndmask_b32_e32 v69, v65, v69, vcc
	v_lshlrev_b32_e32 v69, 2, v69
	v_max_f32_e32 v71, v71, v84
	s_nop 1
	v_mov_b32_dpp v84, v71 row_ror:2 row_mask:0xf bank_mask:0xf
	s_nop 0
	v_cmp_lt_i32_e32 vcc, v85, v70
	s_waitcnt lgkmcnt(0)
	v_max_f32_e32 v84, v84, v84
	v_cndmask_b32_e32 v70, v65, v85, vcc
	v_lshlrev_b32_e32 v70, 2, v70
	v_max_f32_e32 v71, v71, v84
	s_nop 1
	v_mov_b32_dpp v87, v71 row_ror:1 row_mask:0xf bank_mask:0xf
	s_nop 0
	v_mov_b32_e32 v84, 0
	v_mov_b32_e32 v85, 0
	s_waitcnt lgkmcnt(0)
	v_max_f32_e32 v87, v87, v87
	v_max_f32_e32 v71, v71, v87
	v_mul_f32_e32 v87, 0x3b14f209, v71
	v_cmp_lt_f32_e32 vcc, 0, v71
	s_nop 1
	v_cndmask_b32_e32 v71, 1.0, v87, vcc
	v_div_scale_f32 v90, s[12:13], v71, v71, 1.0
	v_rcp_f32_e32 v91, v90
	v_div_scale_f32 v92, vcc, 1.0, v71, 1.0
	v_mov_b32_e32 v87, 0
	v_fma_f32 v93, -v90, v91, 1.0
	v_fmac_f32_e32 v91, v93, v91
	v_mul_f32_e32 v93, v92, v91
	v_fma_f32 v94, -v90, v93, v92
	v_fmac_f32_e32 v93, v94, v91
	v_fma_f32 v90, -v90, v93, v92
	v_div_fmas_f32 v90, v90, v91, v93
	v_div_fixup_f32 v90, v90, v71, 1.0
	v_mul_f32_e32 v58, v58, v90
	v_mul_f32_e32 v59, v59, v90
	v_mul_f32_e32 v72, v72, v90
	v_mul_f32_e32 v73, v73, v90
	v_mul_f32_e32 v76, v76, v90
	v_mul_f32_e32 v77, v77, v90
	v_mul_f32_e32 v80, v80, v90
	v_mul_f32_e32 v81, v81, v90
	v_cvt_pk_fp8_f32 v84, v58, v59
	v_cvt_pk_fp8_f32 v85, v72, v73
	v_cvt_pk_fp8_f32 v86, v76, v77
	v_cvt_pk_fp8_f32 v87, v80, v81
	v_mul_f32_e32 v60, v60, v90
	v_mul_f32_e32 v61, v61, v90
	v_mul_f32_e32 v74, v74, v90
	v_mul_f32_e32 v75, v75, v90
	v_mul_f32_e32 v78, v78, v90
	v_mul_f32_e32 v79, v79, v90
	v_mul_f32_e32 v82, v82, v90
	v_mul_f32_e32 v83, v83, v90
	v_cvt_pk_fp8_f32 v84, v60, v61 op_sel:[0,0,1]
	v_cvt_pk_fp8_f32 v85, v74, v75 op_sel:[0,0,1]
	v_cvt_pk_fp8_f32 v86, v78, v79 op_sel:[0,0,1]
	v_cvt_pk_fp8_f32 v87, v82, v83 op_sel:[0,0,1]
	v_lshlrev_b64 v[60:61], 10, v[88:89]
	v_lshl_add_u64 v[58:59], v[88:89], 3, s[10:11]
	v_lshl_add_u64 v[60:61], v[52:53], 0, v[60:61]
	global_store_dwordx4 v[60:61], v[84:87], off
	s_and_saveexec_b64 s[12:13], s[4:5]
	s_cbranch_execz .Lp1a_471
	global_store_dword v[58:59], v71, off

; DI int vb_n() { return (int)gridDim.x * 2; }
; template <int NR>
; DI void fp8_rows(const float* __restrict__ src, unsigned char* __restrict__ dst, float* __restrict__ scale_out, int lane) {
;     ...
;   for (int r = 0; r < NR; ++r) {
;     float amax = 0.f;
; #pragma unroll
;     for (int i = 0; i < 4; ++i)
;       amax = fmaxf(amax, fmaxf(fmaxf(fabsf(v[r][i].x), fabsf(v[r][i].y)), fmaxf(fabsf(v[r][i].z), fabsf(v[r][i].w))));
; #pragma unroll
;     for (int o = 32; o > 0; o >>= 1) amax = fmaxf(amax, __shfl_xor(amax, o));
;     const float scale = amax > 0.f ? amax * (1.f / 440.f) : 1.f;
;     const float inv = 1.f / scale;
;     u32x4 w;
; #pragma unroll
;     for (int i = 0; i < 4; ++i) {
;       int t = 0;
;       t = __builtin_amdgcn_cvt_pk_fp8_f32(v[r][i].x * inv, v[r][i].y * inv, t, false);
;       t = __builtin_amdgcn_cvt_pk_fp8_f32(v[r][i].z * inv, v[r][i].w * inv, t, true);
;       w[i] = (unsigned)t;
;     }
;     *(u32x4*)(dst + (size_t)r * 1024 + lane * 16) = w;
;     if (lane == 0) scale_out[r] = scale;
;   }
; DI void phase_prep(const Params& p, char* smem, int part, int vb) {
;     ...
;     for (int it0 = vb; it0 < NITEMS; it0 += vb_n()) {
;       int it = it0;
;       if (it < 1024) {
;         int row = it * 16 + wave * 4;
;         fp8_rows<4>(p.pu + (size_t)row * 1024, (unsigned char*)(ws + WS_UBF) + (size_t)row * 1024, (float*)(ws + WS_SU) + row, lane);
;         continue;
;       }
;       it -= 1024;
;       if (it < 1024) {
;         int row = it * 16 + wave * 4;
;         fp8_rows<4>(p.pv + (size_t)row * 1024, (unsigned char*)(ws + WS_VBF) + (size_t)row * 1024, (float*)(ws + WS_SV) + row, lane);
;         continue;
;       }
.Lp1a_475:
	s_or_b64 exec, exec, s[12:13]
	v_max_f32_e64 v16, |v15|, |v15|
	v_max_f32_e64 v17, |v14|, |v14|
	v_max_f32_e32 v16, v17, v16
	v_max_f32_e64 v17, |v11|, |v11|
	v_max_f32_e64 v18, |v10|, |v10|
	v_max_f32_e32 v17, v18, v17
	v_max3_f32 v16, |v12|, |v13|, v16
	v_max3_f32 v17, |v8|, |v9|, v17
	v_max3_f32 v16, v16, 0, v17
	v_max_f32_e64 v17, |v7|, |v7|
	v_max_f32_e64 v18, |v6|, |v6|
	v_max_f32_e32 v17, v18, v17
	s_waitcnt vmcnt(3)
	v_max_f32_e64 v18, |v3|, |v3|
	v_max_f32_e64 v19, |v2|, |v2|
	v_max_f32_e32 v18, v19, v18
	v_max3_f32 v17, |v4|, |v5|, v17
	v_max3_f32 v18, |v0|, |v1|, v18
	v_max3_f32 v16, v16, v17, v18
	v_mov_b32_e32 v17, v16
	s_nop 1
	v_permlane32_swap_b32_e32 v17, v16
	s_nop 1
	v_mov_b32_e32 v18, 0
	v_mov_b32_e32 v19, 0
	s_waitcnt lgkmcnt(0)
	v_max_f32_e32 v17, v17, v17
	v_max_f32_e32 v16, v16, v17
	v_mov_b32_e32 v17, v16
	s_nop 1
	v_permlane16_swap_b32_e32 v17, v16
	s_nop 1
	s_waitcnt lgkmcnt(0)
	v_max_f32_e32 v17, v17, v17
	v_max_f32_e32 v16, v16, v17
	s_nop 1
	v_mov_b32_dpp v17, v16 row_ror:8 row_mask:0xf bank_mask:0xf
	s_nop 0
	s_waitcnt lgkmcnt(0)
	v_max_f32_e32 v17, v17, v17
	v_max_f32_e32 v16, v16, v17
	s_nop 1
	v_mov_b32_dpp v17, v16 row_ror:4 row_mask:0xf bank_mask:0xf
	s_nop 0
	s_waitcnt lgkmcnt(0)
	v_max_f32_e32 v17, v17, v17
	v_max_f32_e32 v16, v16, v17
	s_nop 1
	v_mov_b32_dpp v17, v16 row_ror:2 row_mask:0xf bank_mask:0xf
	s_nop 0
	s_waitcnt lgkmcnt(0)
	v_max_f32_e32 v17, v17, v17
	v_max_f32_e32 v16, v16, v17
	s_nop 1
	v_mov_b32_dpp v17, v16 row_ror:1 row_mask:0xf bank_mask:0xf
	s_nop 0
	s_waitcnt lgkmcnt(0)
	v_max_f32_e32 v17, v17, v17
	v_max_f32_e32 v16, v16, v17
	v_mul_f32_e32 v17, 0x3b14f209, v16
	v_cmp_lt_f32_e32 vcc, 0, v16
	s_nop 1
	v_cndmask_b32_e32 v16, 1.0, v17, vcc
	v_div_scale_f32 v17, s[12:13], v16, v16, 1.0
	v_rcp_f32_e32 v20, v17
	v_div_scale_f32 v21, vcc, 1.0, v16, 1.0
	v_fma_f32 v22, -v17, v20, 1.0
	v_fmac_f32_e32 v20, v22, v20
	v_mul_f32_e32 v22, v21, v20
	v_fma_f32 v23, -v17, v22, v21
	v_fmac_f32_e32 v22, v23, v20
	v_fma_f32 v17, -v17, v22, v21
	v_div_fmas_f32 v17, v17, v20, v22
	v_div_fixup_f32 v17, v17, v16, 1.0
	v_mul_f32_e32 v12, v12, v17
	v_mul_f32_e32 v13, v13, v17
	v_mul_f32_e32 v8, v8, v17
	v_mul_f32_e32 v9, v9, v17
	v_mul_f32_e32 v4, v4, v17
	v_mul_f32_e32 v5, v5, v17
	v_mov_b32_e32 v20, 0
	v_mul_f32_e32 v0, v0, v17
	v_mul_f32_e32 v1, v1, v17
	v_mov_b32_e32 v21, 0
	v_cvt_pk_fp8_f32 v18, v12, v13
	v_cvt_pk_fp8_f32 v19, v8, v9
	v_cvt_pk_fp8_f32 v20, v4, v5
	v_cvt_pk_fp8_f32 v21, v0, v1
	v_mul_f32_e32 v14, v14, v17
	v_mul_f32_e32 v15, v15, v17
	v_mul_f32_e32 v10, v10, v17
	v_mul_f32_e32 v8, v11, v17
	v_mul_f32_e32 v4, v6, v17
	v_mul_f32_e32 v5, v7, v17
	v_mul_f32_e32 v0, v2, v17
	v_mul_f32_e32 v1, v3, v17
	v_cvt_pk_fp8_f32 v18, v14, v15 op_sel:[0,0,1]
	v_cvt_pk_fp8_f32 v19, v10, v8 op_sel:[0,0,1]
	v_cvt_pk_fp8_f32 v20, v4, v5 op_sel:[0,0,1]
	v_cvt_pk_fp8_f32 v21, v0, v1 op_sel:[0,0,1]
	global_store_dwordx4 v[60:61], v[18:21], off offset:3072
	s_and_saveexec_b64 s[12:13], s[4:5]
	s_cbranch_execz .Lp1a_352
	global_store_dword v[58:59], v16, off offset:24
	s_branch .Lp1a_352
